# pre-epilogue barrier: P8 after 7 stores, P1 after 7 stores, EpiRes phases (P5a P7 P9) after the residual loads are issued and before their vmcnt wait
# baseline (speedup 1.0000x reference)
.LBB0_1205:
	s_lshl_b32 s21, s8, 4
	s_or_b32 s28, s21, s65
	s_lshl_b32 s21, s6, 3
	s_or_b32 s73, s21, s62
	s_ashr_i32 s29, s28, 31
	s_ashr_i32 s72, s73, 31
	s_lshl_b64 s[44:45], s[28:29], 7
	s_add_u32 s30, s44, s73
	s_addc_u32 s31, s45, s72
	s_lshl_b64 s[46:47], s[30:31], 10
	v_lshl_add_u64 v[128:129], v[162:163], 0, s[46:47]
	global_load_dwordx4 v[180:183], v[128:129], off
	v_add_co_u32_e32 v128, vcc, s70, v128
	s_or_b32 s30, s28, 1
	s_nop 0
	v_addc_co_u32_e32 v129, vcc, 0, v129, vcc
	global_load_dwordx4 v[184:187], v[128:129], off
	s_ashr_i32 s31, s30, 31
	s_lshl_b64 s[40:41], s[30:31], 7
	s_add_u32 s30, s40, s73
	s_addc_u32 s31, s41, s72
	s_or_b32 s34, s28, 2
	s_ashr_i32 s35, s34, 31
	s_lshl_b64 s[42:43], s[30:31], 10
	s_lshl_b64 s[36:37], s[34:35], 7
	s_add_u32 s30, s36, s73
	s_addc_u32 s31, s37, s72
	s_or_b32 s34, s28, 3
	s_ashr_i32 s35, s34, 31
	v_lshl_add_u64 v[128:129], v[162:163], 0, s[42:43]
	s_lshl_b64 s[38:39], s[30:31], 10
	s_lshl_b64 s[30:31], s[34:35], 7
	v_add_co_u32_e32 v130, vcc, s70, v128
	s_add_u32 s34, s30, s73
	s_nop 0
	v_addc_co_u32_e32 v131, vcc, 0, v129, vcc
	global_load_dwordx4 v[148:151], v[128:129], off
	global_load_dwordx4 v[144:147], v[130:131], off
	v_lshl_add_u64 v[128:129], v[162:163], 0, s[38:39]
	s_addc_u32 s35, s31, s72
	v_add_co_u32_e32 v130, vcc, s70, v128
	s_lshl_b64 s[34:35], s[34:35], 10
	s_nop 0
	v_addc_co_u32_e32 v131, vcc, 0, v129, vcc
	global_load_dwordx4 v[140:143], v[128:129], off
	global_load_dwordx4 v[136:139], v[130:131], off
	v_lshl_add_u64 v[128:129], v[162:163], 0, s[34:35]
	v_add_co_u32_e32 v130, vcc, s70, v128
	v_lshl_add_u64 v[188:189], v[160:161], 0, s[46:47]
	s_nop 0
	v_addc_co_u32_e32 v131, vcc, 0, v129, vcc
	global_load_dwordx4 v[132:135], v[128:129], off
	s_nop 0
	global_load_dwordx4 v[128:131], v[130:131], off
	s_or_b32 s23, s73, 4
	s_add_u32 s44, s44, s23
	s_addc_u32 s45, s45, s72
	s_lshl_b64 s[44:45], s[44:45], 10
	v_lshl_or_b32 v172, s8, 8, v175
	s_mov_b32 s21, s72
	s_and_b64 vcc, exec, s[10:11]
	s_cbranch_vccz .Lepibar_P5a
	s_barrier
.Lepibar_P5a:
	s_waitcnt vmcnt(0)
	v_lshlrev_b32_e32 v190, 16, v180
	v_and_b32_e32 v191, 0xffff0000, v180
	v_lshlrev_b32_e32 v180, 16, v181
	v_and_b32_e32 v181, 0xffff0000, v181
	v_lshlrev_b32_e32 v192, 16, v182
	v_and_b32_e32 v193, 0xffff0000, v182
	v_lshlrev_b32_e32 v182, 16, v183
	v_and_b32_e32 v183, 0xffff0000, v183
	v_pk_add_f32 v[126:127], v[126:127], v[180:181]
	v_pk_add_f32 v[124:125], v[124:125], v[190:191]
	v_pk_add_f32 v[180:181], v[122:123], v[182:183]
	v_pk_add_f32 v[182:183], v[120:121], v[192:193]
	v_mul_f32_e32 v173, v125, v125
	v_mul_f32_e32 v190, v127, v127
	v_mul_f32_e32 v191, v183, v183
	v_mul_f32_e32 v192, v181, v181
	v_lshlrev_b32_e32 v194, 16, v184
	v_and_b32_e32 v195, 0xffff0000, v184
	v_lshlrev_b32_e32 v184, 16, v185
	v_and_b32_e32 v185, 0xffff0000, v185
	v_cvt_pk_bf16_f32 v120, v124, v125
	v_cvt_pk_bf16_f32 v121, v126, v127
	v_fmac_f32_e32 v173, v124, v124
	v_fmac_f32_e32 v190, v126, v126
	v_fmac_f32_e32 v191, v182, v182
	v_fmac_f32_e32 v192, v180, v180
	v_lshlrev_b32_e32 v196, 16, v186
	v_and_b32_e32 v197, 0xffff0000, v186
	v_lshlrev_b32_e32 v186, 16, v187
	v_and_b32_e32 v187, 0xffff0000, v187
	v_cvt_pk_bf16_f32 v122, v182, v183
	v_cvt_pk_bf16_f32 v123, v180, v181
	global_store_dwordx4 v[188:189], v[120:123], off
	v_pk_add_f32 v[118:119], v[118:119], v[184:185]
	v_pk_add_f32 v[116:117], v[116:117], v[194:195]
	v_add_f32_e32 v120, v173, v190
	v_add_f32_e32 v121, v191, v192
	v_add_f32_e32 v122, v120, v121
	v_pk_add_f32 v[120:121], v[114:115], v[186:187]
	v_pk_add_f32 v[114:115], v[112:113], v[196:197]
	v_mul_f32_e32 v112, v117, v117
	v_mul_f32_e32 v113, v119, v119
	v_fmac_f32_e32 v112, v116, v116
	v_fmac_f32_e32 v113, v118, v118
	v_add_f32_e32 v112, v112, v113
	v_mul_f32_e32 v113, v115, v115
	v_mul_f32_e32 v123, v121, v121
	v_fmac_f32_e32 v113, v114, v114
	v_fmac_f32_e32 v123, v120, v120
	v_add_f32_e32 v113, v113, v123
	v_add_f32_e32 v112, v112, v113
	v_add_f32_e32 v113, v122, v112
	v_and_b32_e32 v122, 64, v179
	v_xor_b32_e32 v112, 16, v179
	v_add_u32_e32 v122, 64, v122
	v_cmp_lt_i32_e32 vcc, v112, v122
	v_cvt_pk_bf16_f32 v116, v116, v117
	v_cvt_pk_bf16_f32 v117, v118, v119
	v_cvt_pk_bf16_f32 v118, v114, v115
	v_cvt_pk_bf16_f32 v119, v120, v121
	v_lshl_add_u64 v[120:121], v[160:161], 0, s[44:45]
	s_nop 0
	v_cndmask_b32_e32 v112, v179, v112, vcc
	v_lshlrev_b32_e32 v112, 2, v112
	ds_bpermute_b32 v123, v112, v113
	global_store_dwordx4 v[120:121], v[116:119], off
	s_waitcnt lgkmcnt(0)
	v_add_f32_e32 v114, v113, v123
	v_xor_b32_e32 v113, 32, v179
	v_cmp_lt_i32_e32 vcc, v113, v122
	s_nop 1
	v_cndmask_b32_e32 v113, v179, v113, vcc
	v_lshlrev_b32_e32 v113, 2, v113
	ds_bpermute_b32 v115, v113, v114
	s_and_saveexec_b64 s[44:45], s[2:3]
	s_cbranch_execz .LBB0_1207
	v_ashrrev_i32_e32 v173, 31, v172
	s_waitcnt lgkmcnt(0)
	v_add_f32_e32 v116, v114, v115
	s_lshl_b32 s46, s6, 2
	v_lshlrev_b64 v[114:115], 8, v[172:173]
	s_ashr_i32 s47, s46, 31
	v_lshl_add_u64 v[114:115], s[14:15], 0, v[114:115]
	v_lshl_add_u64 v[114:115], s[46:47], 2, v[114:115]
	s_lshl_b32 s8, s62, 2
	v_lshl_add_u64 v[114:115], v[114:115], 0, s[8:9]
	global_store_dword v[114:115], v116, off

.LBB0_1438:
	s_lshl_b32 s1, s6, 4
	s_or_b32 s24, s1, s47
	s_lshl_b32 s1, s0, 3
	s_or_b32 s19, s1, s44
	s_ashr_i32 s25, s24, 31
	s_ashr_i32 s54, s19, 31
	s_lshl_b64 s[34:35], s[24:25], 7
	s_add_u32 s26, s34, s19
	s_addc_u32 s27, s35, s54
	s_lshl_b64 s[26:27], s[26:27], 10
	v_lshl_add_u64 v[192:193], v[160:161], 0, s[26:27]
	global_load_dwordx4 v[184:187], v[192:193], off
	v_add_co_u32_e32 v128, vcc, s52, v192
	s_or_b32 s26, s24, 1
	s_nop 0
	v_addc_co_u32_e32 v129, vcc, 0, v193, vcc
	global_load_dwordx4 v[188:191], v[128:129], off
	s_ashr_i32 s27, s26, 31
	s_lshl_b64 s[30:31], s[26:27], 7
	s_add_u32 s26, s30, s19
	s_addc_u32 s27, s31, s54
	s_or_b32 s28, s24, 2
	s_ashr_i32 s29, s28, 31
	s_lshl_b64 s[26:27], s[26:27], 10
	s_lshl_b64 s[28:29], s[28:29], 7
	v_lshl_add_u64 v[176:177], v[160:161], 0, s[26:27]
	s_add_u32 s26, s28, s19
	s_addc_u32 s27, s29, s54
	s_or_b32 s56, s24, 3
	s_lshl_b64 s[26:27], s[26:27], 10
	s_ashr_i32 s57, s56, 31
	v_lshl_add_u64 v[174:175], v[160:161], 0, s[26:27]
	s_lshl_b64 s[26:27], s[56:57], 7
	v_add_co_u32_e32 v128, vcc, s52, v176
	s_add_u32 s56, s26, s19
	s_nop 0
	v_addc_co_u32_e32 v129, vcc, 0, v177, vcc
	s_addc_u32 s57, s27, s54
	global_load_dwordx4 v[144:147], v[128:129], off
	v_add_co_u32_e32 v128, vcc, s52, v174
	s_lshl_b64 s[56:57], s[56:57], 10
	s_nop 0
	v_addc_co_u32_e32 v129, vcc, 0, v175, vcc
	v_lshl_add_u64 v[172:173], v[160:161], 0, s[56:57]
	v_add_co_u32_e32 v130, vcc, s52, v172
	global_load_dwordx4 v[148:151], v[176:177], off
	global_load_dwordx4 v[136:139], v[174:175], off
	v_addc_co_u32_e32 v131, vcc, 0, v173, vcc
	global_load_dwordx4 v[132:135], v[172:173], off
	global_load_dwordx4 v[140:143], v[128:129], off
	s_nop 0
	global_load_dwordx4 v[128:131], v[130:131], off
	s_or_b32 s17, s19, 4
	s_add_u32 s34, s34, s17
	s_addc_u32 s35, s35, s54
	s_lshl_b64 s[34:35], s[34:35], 10
	v_lshl_or_b32 v170, s6, 8, v179
	s_mov_b32 s1, s54
	s_and_b64 vcc, exec, s[8:9]
	s_cbranch_vccz .Lepibar_P7
	s_barrier
.Lepibar_P7:
	s_waitcnt vmcnt(0)
	v_lshlrev_b32_e32 v194, 16, v184
	v_and_b32_e32 v195, 0xffff0000, v184
	v_lshlrev_b32_e32 v184, 16, v185
	v_and_b32_e32 v185, 0xffff0000, v185
	v_lshlrev_b32_e32 v196, 16, v186
	v_and_b32_e32 v197, 0xffff0000, v186
	v_lshlrev_b32_e32 v186, 16, v187
	v_and_b32_e32 v187, 0xffff0000, v187
	v_pk_add_f32 v[126:127], v[126:127], v[184:185]
	v_pk_add_f32 v[124:125], v[124:125], v[194:195]
	v_pk_add_f32 v[184:185], v[122:123], v[186:187]
	v_pk_add_f32 v[186:187], v[120:121], v[196:197]
	v_mul_f32_e32 v171, v125, v125
	v_mul_f32_e32 v194, v127, v127
	v_mul_f32_e32 v195, v187, v187
	v_mul_f32_e32 v196, v185, v185
	v_lshlrev_b32_e32 v198, 16, v188
	v_and_b32_e32 v199, 0xffff0000, v188
	v_lshlrev_b32_e32 v188, 16, v189
	v_and_b32_e32 v189, 0xffff0000, v189
	v_cvt_pk_bf16_f32 v120, v124, v125
	v_cvt_pk_bf16_f32 v121, v126, v127
	v_fmac_f32_e32 v171, v124, v124
	v_fmac_f32_e32 v194, v126, v126
	v_fmac_f32_e32 v195, v186, v186
	v_fmac_f32_e32 v196, v184, v184
	v_lshlrev_b32_e32 v200, 16, v190
	v_and_b32_e32 v201, 0xffff0000, v190
	v_lshlrev_b32_e32 v190, 16, v191
	v_and_b32_e32 v191, 0xffff0000, v191
	v_cvt_pk_bf16_f32 v122, v186, v187
	v_cvt_pk_bf16_f32 v123, v184, v185
	global_store_dwordx4 v[192:193], v[120:123], off
	v_pk_add_f32 v[118:119], v[118:119], v[188:189]
	v_pk_add_f32 v[116:117], v[116:117], v[198:199]
	v_add_f32_e32 v120, v171, v194
	v_add_f32_e32 v121, v195, v196
	v_add_f32_e32 v122, v120, v121
	v_pk_add_f32 v[120:121], v[114:115], v[190:191]
	v_pk_add_f32 v[114:115], v[112:113], v[200:201]
	v_mul_f32_e32 v112, v117, v117
	v_mul_f32_e32 v113, v119, v119
	v_fmac_f32_e32 v112, v116, v116
	v_fmac_f32_e32 v113, v118, v118
	v_add_f32_e32 v112, v112, v113
	v_mul_f32_e32 v113, v115, v115
	v_mul_f32_e32 v123, v121, v121
	v_fmac_f32_e32 v113, v114, v114
	v_fmac_f32_e32 v123, v120, v120
	v_add_f32_e32 v113, v113, v123
	v_add_f32_e32 v112, v112, v113
	v_add_f32_e32 v113, v122, v112
	v_and_b32_e32 v122, 64, v183
	v_xor_b32_e32 v112, 16, v183
	v_add_u32_e32 v122, 64, v122
	v_cmp_lt_i32_e32 vcc, v112, v122
	v_cvt_pk_bf16_f32 v116, v116, v117
	v_cvt_pk_bf16_f32 v117, v118, v119
	v_cvt_pk_bf16_f32 v118, v114, v115
	v_cvt_pk_bf16_f32 v119, v120, v121
	v_lshl_add_u64 v[120:121], v[160:161], 0, s[34:35]
	s_nop 0
	v_cndmask_b32_e32 v112, v183, v112, vcc
	v_lshlrev_b32_e32 v112, 2, v112
	ds_bpermute_b32 v123, v112, v113
	global_store_dwordx4 v[120:121], v[116:119], off
	s_waitcnt lgkmcnt(0)
	v_add_f32_e32 v114, v113, v123
	v_xor_b32_e32 v113, 32, v183
	v_cmp_lt_i32_e32 vcc, v113, v122
	s_nop 1
	v_cndmask_b32_e32 v113, v183, v113, vcc
	v_lshlrev_b32_e32 v113, 2, v113
	ds_bpermute_b32 v115, v113, v114
	s_and_saveexec_b64 s[34:35], s[2:3]
	s_cbranch_execz .LBB0_1440
	v_ashrrev_i32_e32 v171, 31, v170
	s_waitcnt lgkmcnt(0)
	v_add_f32_e32 v116, v114, v115
	s_lshl_b32 s56, s0, 2
	v_lshlrev_b64 v[114:115], 8, v[170:171]
	s_ashr_i32 s57, s56, 31
	v_lshl_add_u64 v[114:115], s[12:13], 0, v[114:115]
	v_lshl_add_u64 v[114:115], s[56:57], 2, v[114:115]
	s_lshl_b32 s6, s44, 2
	v_lshl_add_u64 v[114:115], v[114:115], 0, s[6:7]
	global_store_dword v[114:115], v116, off

.LBB0_1628:
	s_lshl_b32 s17, s28, 4
	s_lshl_b32 s22, s0, 3
	s_or_b32 s24, s17, s45
	s_or_b32 s22, s22, s42
	s_ashr_i32 s25, s24, 31
	s_ashr_i32 s23, s22, 31
	s_lshl_b64 s[54:55], s[24:25], 17
	s_lshl_b64 s[26:27], s[22:23], 10
	v_lshl_add_u64 v[128:129], v[160:161], 0, s[54:55]
	v_lshl_add_u64 v[128:129], v[128:129], 0, s[26:27]
	global_load_dwordx4 v[182:185], v[128:129], off
	v_add_co_u32_e32 v128, vcc, s50, v128
	s_or_b32 s22, s24, 1
	s_nop 0
	v_addc_co_u32_e32 v129, vcc, 0, v129, vcc
	global_load_dwordx4 v[186:189], v[128:129], off
	s_ashr_i32 s23, s22, 31
	s_or_b32 s54, s24, 2
	s_lshl_b64 s[22:23], s[22:23], 17
	s_ashr_i32 s55, s54, 31
	v_lshl_add_u64 v[128:129], v[160:161], 0, s[22:23]
	s_or_b32 s56, s24, 3
	s_lshl_b64 s[54:55], s[54:55], 17
	v_lshl_add_u64 v[128:129], v[128:129], 0, s[26:27]
	s_ashr_i32 s57, s56, 31
	v_lshl_add_u64 v[130:131], v[160:161], 0, s[54:55]
	v_add_co_u32_e32 v134, vcc, s50, v128
	s_lshl_b64 s[56:57], s[56:57], 17
	v_lshl_add_u64 v[130:131], v[130:131], 0, s[26:27]
	v_addc_co_u32_e32 v135, vcc, 0, v129, vcc
	v_lshl_add_u64 v[132:133], v[160:161], 0, s[56:57]
	v_add_co_u32_e32 v136, vcc, s50, v130
	v_lshl_add_u64 v[132:133], v[132:133], 0, s[26:27]
	s_nop 0
	v_addc_co_u32_e32 v137, vcc, 0, v131, vcc
	v_add_co_u32_e32 v170, vcc, s50, v132
	v_lshl_or_b32 v172, s28, 8, v176
	s_nop 0
	v_addc_co_u32_e32 v171, vcc, 0, v133, vcc
	global_load_dwordx4 v[148:151], v[128:129], off
	global_load_dwordx4 v[144:147], v[134:135], off
	global_load_dwordx4 v[140:143], v[130:131], off
	s_nop 0
	global_load_dwordx4 v[136:139], v[136:137], off
	s_nop 0
	global_load_dwordx4 v[132:135], v[132:133], off
	s_nop 0
	global_load_dwordx4 v[128:131], v[170:171], off
	v_ashrrev_i32_e32 v173, 31, v172
	v_lshl_or_b32 v170, s0, 8, v175
	v_lshlrev_b64 v[190:191], 13, v[172:173]
	v_ashrrev_i32_e32 v171, 31, v170
	s_lshl_b32 s22, s0, 2
	s_ashr_i32 s23, s22, 31
	s_and_b64 vcc, exec, s[6:7]
	s_cbranch_vccz .Lepibar_P9
	s_barrier
.Lepibar_P9:
	s_waitcnt vmcnt(0)
	v_lshlrev_b32_e32 v192, 16, v182
	v_and_b32_e32 v193, 0xffff0000, v182
	v_lshlrev_b32_e32 v182, 16, v183
	v_and_b32_e32 v183, 0xffff0000, v183
	v_lshlrev_b32_e32 v194, 16, v184
	v_and_b32_e32 v195, 0xffff0000, v184
	v_lshlrev_b32_e32 v184, 16, v185
	v_and_b32_e32 v185, 0xffff0000, v185
	v_pk_add_f32 v[126:127], v[126:127], v[182:183]
	v_pk_add_f32 v[124:125], v[124:125], v[192:193]
	v_pk_add_f32 v[182:183], v[122:123], v[184:185]
	v_pk_add_f32 v[184:185], v[120:121], v[194:195]
	v_lshlrev_b32_e32 v196, 16, v186
	v_and_b32_e32 v197, 0xffff0000, v186
	v_lshlrev_b32_e32 v186, 16, v187
	v_and_b32_e32 v187, 0xffff0000, v187
	v_mul_f32_e32 v181, v125, v125
	v_mul_f32_e32 v192, v127, v127
	v_mul_f32_e32 v193, v185, v185
	v_mul_f32_e32 v194, v183, v183
	v_lshlrev_b32_e32 v198, 16, v188
	v_and_b32_e32 v199, 0xffff0000, v188
	v_pk_add_f32 v[118:119], v[118:119], v[186:187]
	v_fmac_f32_e32 v181, v124, v124
	v_fmac_f32_e32 v192, v126, v126
	v_fmac_f32_e32 v193, v184, v184
	v_fmac_f32_e32 v194, v182, v182
	v_pk_add_f32 v[116:117], v[116:117], v[196:197]
	v_lshlrev_b32_e32 v188, 16, v189
	v_and_b32_e32 v189, 0xffff0000, v189
	v_cvt_pk_bf16_f32 v120, v124, v125
	v_cvt_pk_bf16_f32 v121, v126, v127
	v_add_f32_e32 v124, v181, v192
	v_add_f32_e32 v125, v193, v194
	v_pk_add_f32 v[126:127], v[112:113], v[198:199]
	v_mul_f32_e32 v112, v117, v117
	v_mul_f32_e32 v113, v119, v119
	v_add_f32_e32 v181, v124, v125
	v_pk_add_f32 v[124:125], v[114:115], v[188:189]
	v_fmac_f32_e32 v112, v116, v116
	v_fmac_f32_e32 v113, v118, v118
	v_add_f32_e32 v112, v112, v113
	v_mul_f32_e32 v113, v127, v127
	v_mul_f32_e32 v114, v125, v125
	v_fmac_f32_e32 v113, v126, v126
	v_fmac_f32_e32 v114, v124, v124
	v_add_f32_e32 v113, v113, v114
	v_add_f32_e32 v112, v112, v113
	v_and_b32_e32 v113, 64, v180
	v_add_f32_e32 v115, v181, v112
	v_xor_b32_e32 v112, 16, v180
	v_add_u32_e32 v181, 64, v113
	v_cmp_lt_i32_e32 vcc, v112, v181
	v_cvt_pk_bf16_f32 v122, v184, v185
	v_cvt_pk_bf16_f32 v123, v182, v183
	s_nop 1
	v_cndmask_b32_e32 v112, v180, v112, vcc
	v_lshlrev_b32_e32 v114, 2, v112
	ds_bpermute_b32 v184, v114, v115
	v_lshl_add_u64 v[112:113], s[10:11], 0, v[190:191]
	v_lshl_add_u64 v[182:183], v[170:171], 1, v[112:113]
	v_xor_b32_e32 v113, 32, v180
	v_cmp_lt_i32_e32 vcc, v113, v181
	s_waitcnt lgkmcnt(0)
	v_add_f32_e32 v112, v115, v184
	global_store_dwordx4 v[182:183], v[120:123], off
	v_cndmask_b32_e32 v113, v180, v113, vcc
	v_lshlrev_b32_e32 v115, 2, v113
	ds_bpermute_b32 v113, v115, v112
	v_cvt_pk_bf16_f32 v116, v116, v117
	v_cvt_pk_bf16_f32 v117, v118, v119
	v_cvt_pk_bf16_f32 v118, v126, v127
	v_cvt_pk_bf16_f32 v119, v124, v125
	global_store_dwordx4 v[182:183], v[116:119], off offset:256
	s_and_saveexec_b64 s[28:29], s[2:3]
	s_cbranch_execz .LBB0_1630
	v_lshlrev_b64 v[116:117], 8, v[172:173]
	v_lshl_add_u64 v[116:117], s[12:13], 0, v[116:117]
	v_lshl_add_u64 v[116:117], s[22:23], 2, v[116:117]
	s_lshl_b32 s0, s42, 2
	v_lshl_add_u64 v[116:117], v[116:117], 0, s[0:1]
	s_waitcnt lgkmcnt(0)
	v_add_f32_e32 v112, v112, v113
	global_store_dword v[116:117], v112, off
